# sparse inner loop: per-phase s_setprio (1 around the QK and PV MFMA blocks, 0 around the softmax VALU block) so the partner wave's MFMAs are not starved by this wave's exp stream; v75 otherwise
# speedup vs baseline: 1.0059x; 1.0026x over previous
.LBB0_841:
	s_setprio 1
	s_waitcnt lgkmcnt(3)
	v_mfma_f32_32x32x16_bf16 v[64:79], v[224:227], v[112:115], 0
	ds_read_b128 v[224:227], v171
	s_waitcnt lgkmcnt(3)
	v_mfma_f32_32x32x16_bf16 v[64:79], v[228:231], v[116:119], v[64:79]
	ds_read_b128 v[228:231], v175
	s_waitcnt lgkmcnt(3)
	v_mfma_f32_32x32x16_bf16 v[64:79], v[232:235], v[120:123], v[64:79]
	ds_read_b128 v[232:235], v176
	s_waitcnt lgkmcnt(3)
	v_mfma_f32_32x32x16_bf16 v[64:79], v[236:239], v[124:127], v[64:79]
	ds_read_b128 v[236:239], v185
	ds_read_b64_tr_b16 v[208:209], v241
	ds_read_b64_tr_b16 v[210:211], v241 offset:2048
	s_waitcnt lgkmcnt(5)
	v_mfma_f32_32x32x16_bf16 v[64:79], v[224:227], v[128:131], v[64:79]
	ds_read_b64_tr_b16 v[212:213], v241 offset:256
	ds_read_b64_tr_b16 v[214:215], v241 offset:2304
	s_waitcnt lgkmcnt(6)
	v_mfma_f32_32x32x16_bf16 v[64:79], v[228:231], v[132:135], v[64:79]
	ds_read_b64_tr_b16 v[216:217], v241 offset:512
	ds_read_b64_tr_b16 v[218:219], v241 offset:2560
	s_waitcnt lgkmcnt(7)
	v_mfma_f32_32x32x16_bf16 v[64:79], v[232:235], v[136:139], v[64:79]
	ds_read_b64_tr_b16 v[220:221], v241 offset:768
	ds_read_b64_tr_b16 v[222:223], v241 offset:2816
	s_waitcnt lgkmcnt(8)
	v_mfma_f32_32x32x16_bf16 v[64:79], v[236:239], v[140:143], v[64:79]
	s_setprio 0
	v_add_u32_e32 v155, 0x2000, v155
	v_add_u32_e32 v159, 0x2000, v159
	v_add_u32_e32 v163, 0x2000, v163
	v_add_u32_e32 v167, 0x2000, v167
	v_add_u32_e32 v171, 0x2000, v171
	v_add_u32_e32 v175, 0x2000, v175
	v_add_u32_e32 v176, 0x2000, v176
	v_add_u32_e32 v185, 0x2000, v185
	s_nop 3
	v_exp_f32_e32 v224, v64
	v_exp_f32_e32 v225, v65
	v_exp_f32_e32 v226, v66
	v_exp_f32_e32 v227, v67
	v_exp_f32_e32 v228, v68
	v_exp_f32_e32 v229, v69
	v_exp_f32_e32 v230, v70
	v_exp_f32_e32 v231, v71
	v_exp_f32_e32 v232, v72
	v_exp_f32_e32 v233, v73
	v_exp_f32_e32 v234, v74
	v_exp_f32_e32 v235, v75
	v_exp_f32_e32 v236, v76
	v_exp_f32_e32 v237, v77
	v_exp_f32_e32 v238, v78
	v_exp_f32_e32 v239, v79
	v_cvt_pk_bf16_f32 v64, v224, v225
	v_cvt_pk_bf16_f32 v65, v226, v227
	v_cvt_pk_bf16_f32 v66, v228, v229
	v_cvt_pk_bf16_f32 v67, v230, v231
	v_cvt_pk_bf16_f32 v68, v232, v233
	v_cvt_pk_bf16_f32 v69, v234, v235
	v_cvt_pk_bf16_f32 v70, v236, v237
	v_cvt_pk_bf16_f32 v71, v238, v239
	s_setprio 1
	s_waitcnt lgkmcnt(6)
	v_mfma_f32_32x32x16_bf16 v[48:63], v[208:211], v[64:67], v[48:63]
	ds_read_b64_tr_b16 v[208:209], v241 offset:4096
	ds_read_b64_tr_b16 v[210:211], v241 offset:6144
	v_add_f32_e32 v240, 0, v224
	v_add_f32_e32 v240, v225, v240
	v_add_f32_e32 v240, v226, v240
	v_add_f32_e32 v240, v227, v240
	v_add_f32_e32 v240, v228, v240
	s_waitcnt lgkmcnt(6)
	v_mfma_f32_32x32x16_bf16 v[32:47], v[212:215], v[64:67], v[32:47]
	ds_read_b64_tr_b16 v[212:213], v241 offset:4352
	ds_read_b64_tr_b16 v[214:215], v241 offset:6400
	v_add_f32_e32 v240, v229, v240
	v_add_f32_e32 v240, v230, v240
	v_add_f32_e32 v240, v231, v240
	v_add_f32_e32 v240, v232, v240
	s_waitcnt lgkmcnt(6)
	v_mfma_f32_32x32x16_bf16 v[16:31], v[216:219], v[64:67], v[16:31]
	ds_read_b64_tr_b16 v[216:217], v241 offset:4608
	ds_read_b64_tr_b16 v[218:219], v241 offset:6656
	v_add_f32_e32 v240, v233, v240
	v_add_f32_e32 v240, v234, v240
	v_add_f32_e32 v240, v235, v240
	v_add_f32_e32 v240, v236, v240
	s_waitcnt lgkmcnt(6)
	v_mfma_f32_32x32x16_bf16 v[0:15], v[220:223], v[64:67], v[0:15]
	ds_read_b64_tr_b16 v[220:221], v241 offset:4864
	ds_read_b64_tr_b16 v[222:223], v241 offset:6912
	v_add_f32_e32 v240, v237, v240
	v_add_f32_e32 v240, v238, v240
	v_add_f32_e32 v240, v239, v240
	v_add_f32_e32 v151, v151, v240
	s_waitcnt lgkmcnt(6)
	v_mfma_f32_32x32x16_bf16 v[48:63], v[208:211], v[68:71], v[48:63]
	ds_read_b128 v[224:227], v155
	s_waitcnt lgkmcnt(5)
	v_mfma_f32_32x32x16_bf16 v[32:47], v[212:215], v[68:71], v[32:47]
	ds_read_b128 v[228:231], v159
	s_waitcnt lgkmcnt(4)
	v_mfma_f32_32x32x16_bf16 v[16:31], v[216:219], v[68:71], v[16:31]
	ds_read_b128 v[232:235], v163
	s_waitcnt lgkmcnt(3)
	v_mfma_f32_32x32x16_bf16 v[0:15], v[220:223], v[68:71], v[0:15]
	ds_read_b128 v[236:239], v167
	v_add_u32_e32 v241, 0x2000, v241
	s_addk_i32 s8, 0x2000
	s_cmp_lg_u32 s8, 0x10000
	s_cbranch_scc1 .LBB0_841
	s_waitcnt lgkmcnt(0)
	s_setprio 0
	ds_bpermute_b32 v66, v191, v151
	v_lshrrev_b32_e32 v65, 2, v207
	v_cmp_ne_u32_e32 vcc, -1, v207
	v_and_b32_e32 v64, 3, v207
	v_lshl_add_u32 v65, s68, 13, v65
	v_mad_u64_u32 v[64:65], s[8:9], v65, 3, v[64:65]
	s_and_b64 s[30:31], vcc, s[4:5]
	s_and_saveexec_b64 s[8:9], s[30:31]
	s_cbranch_execz .LBB0_844
	v_ashrrev_i32_e32 v65, 31, v64
	s_waitcnt lgkmcnt(0)
	v_add_f32_e32 v68, v151, v66
	v_lshl_add_u64 v[66:67], v[64:65], 2, s[36:37]
	global_store_dword v[66:67], v68, off
	s_add_u32 s98, s98, 1
